# P10 gate/up GEMM: LDS-DMA staging as 8-row x 128-B full-line pieces (row-major [row][128B] LDS image, chunk XOR row&7) instead of 16x64B subtiles
# speedup vs baseline: 1.0005x; 1.0005x over previous
; #define PG8_STAGE(bufoff, gbase, voff) do { _Pragma("unroll") for (int _i = 0; _i < 2; ++_i) \
;         __builtin_amdgcn_global_load_lds((const unsigned*)((const char*)(gbase) + (voff)[_i]), (PG8_LAS unsigned*)(lds + (bufoff) + ldsw + _i * 8192), 16, 0, 0); } while (0)
; #define PG8_WAIT_V(n) asm volatile("s_waitcnt vmcnt(" #n ")" ::: "memory")
; #define PG8_BAR __builtin_amdgcn_s_barrier()
; template <class Epi, class Sched, bool ALIGN_EPI = false, bool SP2 = false>
; __device__ __forceinline__ void gemm_phase(PG8_LAS unsigned char* lds, const Gemm g, const Sched& S, const Epi& E) {
;     int tid_ = threadIdx.x; asm volatile("" : "+v"(tid_));
;     const int tid = tid_, wid = __builtin_amdgcn_readfirstlane(tid >> 6), lane = tid & 63, wr = wid >> 2, wc = wid & 3, fr = lane & 15, fq = lane >> 4;
;     const int K = g.ld, nt = g.K / BK;
;     unsigned voffA[2], voffB[2];
;     constexpr bool BADJ = badj_of<Epi>::v;
; #pragma unroll
;     for (int i = 0; i < 2; ++i) { int R, C; stage_rc(tid * 16 + i * 8192, R, C); const int Rb = BADJ ? ((R >> 5) * 64 + perm32(R & 31)) : (Epi::PERM ? ((R & ~31) + perm32(R & 31)) : R);
;         voffA[i] = (unsigned)(R * K + C) * 2u; voffB[i] = (unsigned)(Rb * K + C) * 2u; }
;     const size_t kstep = (size_t)(BK * 2);
;     const size_t hstep = (size_t)HALF * K * 2;
;     const size_t hstepB = BADJ ? (size_t)32 * K * 2 : hstep;
;     const size_t tstep = 2 * hstep;
;     const unsigned ldsw = (unsigned)wid * 1024u;
;     const int aoff = lds_byte(wr * 64 + fr, fq * 8), boff = lds_byte(wc * 32 + fr, fq * 8);
;     ...
;     if constexpr (SP2) {
;         PG8_STAGE(PG8_SB(0, 0), cB, voffB); PG8_STAGE(PG8_SB(0, 1), cB + hstepB, voffB); PG8_STAGE(PG8_SA(0, 0), cA, voffA); PG8_STAGE(PG8_SA(0, 1), cA + hstep, voffA);
;         if (wr == 1) PG8_BAR;
;         PG8_WAIT_V(2); PG8_BAR;
;         PG8_STAGE(PG8_SB(1, 0), cB + kstep, voffB); PG8_STAGE(PG8_SA(1, 0), cA + kstep, voffA); PG8_STAGE(PG8_SB(1, 1), cB + hstepB + kstep, voffB);
;         PG8_WAIT_V(6); PG8_BAR;
.LBB0_1875:
	s_cmp_lt_i32 s86, 11
	s_cselect_b64 s[0:1], -1, 0
	s_cmp_gt_i32 s87, 10
	s_cselect_b64 s[4:5], -1, 0
	s_and_b64 s[0:1], s[0:1], s[4:5]
	s_andn2_b64 vcc, exec, s[0:1]
	s_cbranch_vccnz .LBB0_2143
	s_add_u32 s22, s82, 0xbc00000
	v_mov_b32_e32 v1, v0
	s_addc_u32 s23, s83, 0
	s_waitcnt vmcnt(0)
	v_mov_b32_e32 v12, v0
	s_cmpk_gt_i32 s95, 0xabf
	v_readfirstlane_b32 s0, v12
	s_cbranch_scc1 .LBB0_1896
	v_lshrrev_b32_e32 v226, 3, v12
	v_and_b32_e32 v227, 7, v12
	v_and_b32_e32 v228, 7, v226
	v_xor_b32_e32 v227, v227, v228
	v_lshlrev_b32_e32 v227, 4, v227
	v_mov_b32_e32 v229, 0x2100
	v_mad_u32_u24 v230, v226, v229, v227
	v_add_u32_e32 v231, 0x84000, v230
	v_and_b32_e32 v232, 3, v226
	v_bfe_u32 v233, v226, 2, 2
	v_lshl_or_b32 v232, v233, 3, v232
	v_bfe_u32 v233, v226, 4, 1
	v_lshl_or_b32 v232, v233, 2, v232
	v_and_b32_e32 v233, 32, v226
	v_or_b32_e32 v232, v232, v233
	v_mov_b32_e32 v229, 0x2100
	v_mad_u32_u24 v234, v232, v229, v227
	v_add_u32_e32 v235, 0x84000, v234
	v_and_b32_e32 v236, 15, v12
	v_bfe_u32 v237, v12, 4, 2
	v_and_b32_e32 v238, 7, v236
	v_xor_b32_e32 v237, v237, v238
	v_lshlrev_b32_e32 v237, 4, v237
	v_lshl_or_b32 v236, v236, 7, v237
	v_lshlrev_b32_e32 v1, 4, v12
	v_add_u32_e32 v2, 0x2000, v1
	s_waitcnt lgkmcnt(0)
	v_ashrrev_i32_e32 v3, 31, v2
	v_lshrrev_b32_e32 v3, 22, v3
	v_add_u32_e32 v3, v2, v3
	v_ashrrev_i32_e32 v10, 10, v3
	v_mul_i32_i24_e32 v3, 0x400, v10
	v_sub_u32_e32 v2, v2, v3
	v_lshrrev_b32_e32 v3, 4, v2
	v_bitop3_b32 v2, v3, v2, 32 bitop3:0x6c
	v_ashrrev_i32_e32 v3, 31, v2
	v_lshrrev_b32_e32 v3, 26, v3
	v_add_u32_e32 v3, v2, v3
	v_lshlrev_b32_e32 v4, 3, v10
	v_ashrrev_i32_e32 v11, 6, v3
	v_and_b32_e32 v4, -16, v4
	v_add_u32_e32 v4, v11, v4
	v_and_b32_e32 v5, 3, v11
	s_mov_b32 s6, 0x1ffffe0
	v_lshrrev_b32_e32 v6, 2, v4
	v_lshlrev_b32_e32 v7, 1, v4
	v_and_b32_e32 v3, 0xc0, v3
	v_and_or_b32 v5, v4, s6, v5
	v_and_b32_e32 v6, 4, v6
	v_and_b32_e32 v7, 24, v7
	v_sub_u32_e32 v2, v2, v3
	v_mov_b32_e32 v3, 1
	v_or3_b32 v5, v5, v6, v7
	v_lshlrev_b32_e32 v6, 5, v10
	v_ashrrev_i16_sdwa v2, v3, sext(v2) dst_sel:DWORD dst_unused:UNUSED_PAD src0_sel:DWORD src1_sel:BYTE_0
	s_movk_i32 s1, 0x1080
	v_and_b32_e32 v13, 32, v6
	v_bfe_i32 v14, v2, 0, 16
	v_mul_lo_u32 v5, v5, s1
	v_add_u32_e32 v2, v13, v14
	v_mul_lo_u32 v4, v4, s1
	v_mov_b32_e32 v130, v235
	v_mov_b32_e32 v132, v231
	v_bfe_i32 v2, v12, 27, 1
	v_lshrrev_b32_e32 v2, 22, v2
	v_add_u32_e32 v2, v1, v2
	v_and_b32_e32 v2, 0xfffffc00, v2
	v_sub_u32_e32 v1, v1, v2
	v_lshrrev_b32_e32 v2, 4, v1
	v_ashrrev_i32_e32 v4, 31, v12
	v_bitop3_b32 v1, v2, v1, 32 bitop3:0x6c
	v_lshrrev_b32_e32 v4, 26, v4
	v_ashrrev_i32_e32 v2, 31, v1
	v_add_u32_e32 v4, v12, v4
	v_lshrrev_b32_e32 v2, 26, v2
	v_ashrrev_i32_e32 v16, 6, v4
	v_add_u32_e32 v2, v1, v2
	v_lshlrev_b32_e32 v4, 3, v16
	v_ashrrev_i32_e32 v15, 6, v2
	v_and_b32_e32 v4, -16, v4
	v_add_u32_e32 v4, v15, v4
	v_and_b32_e32 v5, 3, v15
	s_ashr_i32 s24, s95, 31
	v_and_or_b32 v5, v4, s6, v5
	s_lshr_b32 s6, s24, 29
	s_add_i32 s6, s95, s6
	s_ashr_i32 s5, s0, 6
	s_ashr_i32 s7, s6, 3
	s_and_b32 s6, s6, -8
	s_ashr_i32 s4, s0, 8
	s_lshl_b32 s2, s5, 10
	s_sub_i32 s6, s95, s6
	s_cmp_lt_i32 s6, 0
	s_movk_i32 s25, 0x159
	s_cselect_b32 s8, s25, 0x158
	s_mul_i32 s6, s6, s8
	s_add_i32 s6, s6, s7
	s_mul_hi_i32 s7, s6, 0x2fa0be83
	s_lshr_b32 s8, s7, 31
	s_ashr_i32 s7, s7, 7
	s_add_i32 s7, s7, s8
	s_lshl_b32 s8, s7, 3
	s_mulk_i32 s7, 0x2b0
	s_sub_i32 s6, s6, s7
	s_sext_i32_i16 s7, s6
	s_bfe_u32 s7, s7, 0x3001c
	s_add_i32 s7, s6, s7
	s_sext_i32_i16 s9, s7
	s_and_b32 s7, s7, 0xfff8
	s_sub_i32 s6, s6, s7
	v_lshrrev_b32_e32 v6, 2, v4
	v_lshlrev_b32_e32 v7, 1, v4
	v_and_b32_e32 v2, 0xc0, v2
	s_sext_i32_i16 s6, s6
	v_and_b32_e32 v6, 4, v6
	v_and_b32_e32 v7, 24, v7
	v_sub_u32_e32 v1, v1, v2
	s_add_i32 s40, s8, s6
	s_ashr_i32 s6, s9, 3
	v_or3_b32 v5, v5, v6, v7
	v_lshlrev_b32_e32 v6, 5, v16
	v_ashrrev_i16_sdwa v1, v3, sext(v1) dst_sel:DWORD dst_unused:UNUSED_PAD src0_sel:DWORD src1_sel:BYTE_0
	s_lshr_b32 s10, s9, 3
	s_mul_hi_i32 s7, s6, 0x210000
	s_mul_i32 s6, s6, 0x210000
	v_and_b32_e32 v17, 32, v6
	v_bfe_i32 v18, v1, 0, 16
	s_add_u32 s16, s22, s6
	v_mul_lo_u32 v5, v5, s1
	v_add_u32_e32 v1, v17, v18
	s_addc_u32 s17, s23, s7
	s_add_i32 s26, s2, 0
	v_mov_b32_e32 v134, v234
	s_add_i32 m0, s26, 0x10000
	s_mul_i32 s11, s40, 0x210000
	global_load_lds_dwordx4 v134, s[16:17]
	s_add_i32 m0, s26, 0x12000
	s_add_u32 s6, s16, 0x108000
	global_load_lds_dwordx4 v130, s[16:17]
	s_addc_u32 s7, s17, 0
	s_add_i32 m0, s26, 0x14000
	s_mul_hi_i32 s8, s40, 0x210000
	global_load_lds_dwordx4 v134, s[6:7]
	s_add_i32 m0, s26, 0x16000
	v_mul_lo_u32 v2, v4, s1
	global_load_lds_dwordx4 v130, s[6:7]
	v_readlane_b32 s6, v252, 36
	s_add_u32 s14, s6, s11
	v_readlane_b32 s6, v252, 37
	s_addc_u32 s15, s6, s8
	s_add_i32 s27, s26, 0x2000
	v_mov_b32_e32 v136, v230
	s_mov_b32 m0, s26
	s_add_u32 s6, s14, 0x108000
	global_load_lds_dwordx4 v136, s[14:15]
	s_mov_b32 m0, s27
	s_addc_u32 s7, s15, 0
	s_add_i32 s28, s26, 0x4000
	global_load_lds_dwordx4 v132, s[14:15]
	s_mov_b32 m0, s28
	s_add_i32 s29, s26, 0x6000
	global_load_lds_dwordx4 v136, s[6:7]
	s_mov_b32 m0, s29
	v_mov_b32_e32 v135, 0
	global_load_lds_dwordx4 v132, s[6:7]
	v_mov_b32_e32 v131, v135
	v_mov_b32_e32 v137, v135
	v_mov_b32_e32 v133, v135
	s_cmp_eq_u32 s4, 1
	s_mov_b32 s30, 0
	v_lshl_add_u64 v[8:9], s[16:17], 0, v[134:135]
	v_lshl_add_u64 v[6:7], s[16:17], 0, v[130:131]
	v_lshl_add_u64 v[2:3], s[14:15], 0, v[136:137]
	s_cselect_b64 s[6:7], -1, 0
	s_cmp_lg_u32 s4, 1
	v_lshl_add_u64 v[4:5], s[14:15], 0, v[132:133]
	s_cbranch_scc1 .LBB0_1879
	s_barrier
; #define PG8_STAGE(bufoff, gbase, voff) do { _Pragma("unroll") for (int _i = 0; _i < 2; ++_i) \
;         __builtin_amdgcn_global_load_lds((const unsigned*)((const char*)(gbase) + (voff)[_i]), (PG8_LAS unsigned*)(lds + (bufoff) + ldsw + _i * 8192), 16, 0, 0); } while (0)
; #define PG8_WAIT_V(n) asm volatile("s_waitcnt vmcnt(" #n ")" ::: "memory")
; #define PG8_BAR __builtin_amdgcn_s_barrier()
; template <class Epi, class Sched, bool ALIGN_EPI = false, bool SP2 = false>
; __device__ __forceinline__ void gemm_phase(PG8_LAS unsigned char* lds, const Gemm g, const Sched& S, const Epi& E) {
;     ...
;     const int aoff = lds_byte(wr * 64 + fr, fq * 8), boff = lds_byte(wc * 32 + fr, fq * 8);
;     ...
;         PG8_STAGE(PG8_SB(1, 0), cB + kstep, voffB); PG8_STAGE(PG8_SA(1, 0), cA + kstep, voffA); PG8_STAGE(PG8_SB(1, 1), cB + hstepB + kstep, voffB);
;         PG8_WAIT_V(6); PG8_BAR;
.LBB0_1879:
	s_lshl_b32 s5, s5, 5
	s_mov_b64 s[8:9], 0x80
	s_and_b32 s18, s5, 0x60
	s_add_i32 m0, s26, 0x18000
	v_lshl_add_u64 v[8:9], v[8:9], 0, s[8:9]
	s_lshl_b32 s11, s4, 13
	s_lshl_b32 s5, s18, 7
	s_waitcnt vmcnt(2)
	s_barrier
	global_load_lds_dwordx4 v[8:9], off
	v_lshl_add_u64 v[6:7], v[6:7], 0, s[8:9]
	s_add_i32 m0, s26, 0x1a000
	s_add_i32 s31, s26, 0x8000
	s_add_i32 s33, s26, 0xa000
	global_load_lds_dwordx4 v[6:7], off
	v_lshl_add_u64 v[2:3], v[2:3], 0, s[8:9]
	s_mov_b32 m0, s31
	s_add_u32 s12, s16, 0x108080
	global_load_lds_dwordx4 v[2:3], off
	v_lshl_add_u64 v[2:3], v[4:5], 0, s[8:9]
	s_mov_b32 m0, s33
	s_addc_u32 s13, s17, 0
	global_load_lds_dwordx4 v[2:3], off
	s_add_i32 m0, s26, 0x1c000
	v_lshl_add_u64 v[2:3], s[12:13], 0, v[134:135]
	global_load_lds_dwordx4 v[2:3], off
	v_lshl_add_u64 v[2:3], s[12:13], 0, v[130:131]
	s_add_i32 m0, s26, 0x1e000
	s_cmpk_lt_u32 s0, 0x100
	global_load_lds_dwordx4 v[2:3], off
	v_lshrrev_b32_e32 v3, 1, v12
	v_and_b32_e32 v3, 24, v3
	v_and_b32_e32 v2, 15, v12
	v_lshlrev_b32_e32 v4, 1, v3
	v_lshl_or_b32 v1, s4, 6, v2
	v_lshl_or_b32 v2, v2, 6, v4
	v_lshlrev_b32_e32 v4, 2, v12
	v_and_b32_e32 v4, 32, v4
	v_or_b32_e32 v5, s11, v236
	v_or_b32_e32 v150, s5, v236
	v_or_b32_e32 v151, s18, v3
	v_lshrrev_b32_e32 v3, 1, v16
	v_mul_lo_u32 v2, v15, s1
	s_mov_b32 s0, 0x10800
	v_mad_u64_u32 v[2:3], s[12:13], v3, s0, v[2:3]
	v_or_b32_e32 v2, v2, v17
	s_mov_b64 s[4:5], 0x108080
	v_mov_b32_e32 v2, v230
	v_mov_b32_e32 v3, v135
	v_lshl_add_u64 v[138:139], v[2:3], 0, s[4:5]
	v_lshrrev_b32_e32 v3, 1, v10
	v_mul_lo_u32 v2, v11, s1
	v_mad_u64_u32 v[2:3], s[0:1], v3, s0, v[2:3]
	s_waitcnt vmcnt(6)
	v_or_b32_e32 v2, v2, v13
	s_sext_i32_i16 s41, s10
	s_cselect_b64 s[10:11], -1, 0
	v_mov_b32_e32 v2, v231
	v_mov_b32_e32 v3, v135
	s_add_i32 s35, 0, 0x10000
	s_add_i32 s36, 0, 0x14000
	s_ashr_i32 s34, s3, 31
	v_lshl_add_u64 v[140:141], v[2:3], 0, s[4:5]
	v_mov_b64_e32 v[142:143], 0xac0
	v_mov_b64_e32 v[144:145], 0xabf
	v_add_u32_e32 v152, s35, v150
	v_add_u32_e32 v153, s36, v150
	v_add_u32_e32 v154, 0, v5
	v_xor_b32_e32 v241, 64, v152
	v_xor_b32_e32 v242, 64, v153
	v_xor_b32_e32 v243, 64, v154
	v_xor_b32_e32 v244, 64, v150
	s_movk_i32 s37, 0x5600
	s_barrier
	s_branch .LBB0_1882

; #define PG8_STAGE(bufoff, gbase, voff) do { _Pragma("unroll") for (int _i = 0; _i < 2; ++_i) \
;         __builtin_amdgcn_global_load_lds((const unsigned*)((const char*)(gbase) + (voff)[_i]), (PG8_LAS unsigned*)(lds + (bufoff) + ldsw + _i * 8192), 16, 0, 0); } while (0)
; #define PG8_LDA(dst, b, h) do { _Pragma("unroll") for (int m = 0; m < 4; ++m) _Pragma("unroll") for (int k = 0; k < 2; ++k) dst[m][k] = *(const PG8_LAS bf16x8*)(lds + PG8_SA(b, h) + aoff + m * 2048 + k * 1024); } while (0)
; #define PG8_LDB(dst, b, h) do { _Pragma("unroll") for (int n = 0; n < 2; ++n) _Pragma("unroll") for (int k = 0; k < 2; ++k) dst[n][k] = *(const PG8_LAS bf16x8*)(lds + PG8_SB(b, h) + boff + n * 2048 + k * 1024); } while (0)
; #define PG8_MMA(ai, bj, At, Bt) do { __builtin_amdgcn_s_setprio(1); _Pragma("unroll") for (int m = 0; m < 4; ++m) _Pragma("unroll") for (int n = 0; n < 2; ++n) _Pragma("unroll") for (int k = 0; k < 2; ++k) \
;         acc[ai][bj][m][n] = __builtin_amdgcn_mfma_f32_16x16x32_bf16(Bt[n][k], At[m][k], acc[ai][bj][m][n], 0, 0, 0); __builtin_amdgcn_s_setprio(0); } while (0)
; template <class Epi, class Sched, bool ALIGN_EPI = false, bool SP2 = false>
; __device__ __forceinline__ void gemm_phase(PG8_LAS unsigned char* lds, const Gemm g, const Sched& S, const Epi& E) {
;     ...
;             if constexpr (SP2) {
;             PG8_LDB(B0, 0, 0); PG8_LDB(B1, 0, 1); PG8_SCHED; PG8_LDA(At, 0, 0); PG8_STAGE(PG8_SA(1, 1), a1 + hstep, voffA);
;             PG8_WAIT_V(8); PG8_WAIT_L(0); PG8_BAR; PG8_MMA(0, 0, At, B0); PG8_MMA(0, 1, At, B1); PG8_BAR; PG8_SCHED;
;             PG8_LDA(At, 0, 1); PG8_STAGE(PG8_SB(0, 0), b2, voffB); PG8_STAGE(PG8_SB(0, 1), b2 + hstepB, voffB); PG8_STAGE(PG8_SA(0, 0), a2, voffA);
;             PG8_WAIT_V(8); PG8_WAIT_L(0); PG8_BAR; PG8_MMA(1, 0, At, B0); PG8_MMA(1, 1, At, B1); PG8_BAR; PG8_SCHED;
;             PG8_LDB(B0, 1, 0); PG8_LDB(B1, 1, 1); PG8_SCHED; PG8_LDA(At, 1, 0); PG8_STAGE(PG8_SA(0, 1), a2 + hstep, voffA);
;             PG8_WAIT_V(8); PG8_WAIT_L(0); PG8_BAR; PG8_MMA(0, 0, At, B0); PG8_MMA(0, 1, At, B1); PG8_BAR; PG8_SCHED;
;             PG8_LDA(At, 1, 1); PG8_STAGE(PG8_SB(1, 0), b3, voffB); PG8_STAGE(PG8_SB(1, 1), b3 + hstepB, voffB); PG8_STAGE(PG8_SA(1, 0), a3, voffA);
;             PG8_WAIT_V(8); PG8_WAIT_L(0); PG8_BAR; PG8_MMA(1, 0, At, B0); PG8_MMA(1, 1, At, B1); PG8_BAR; PG8_SCHED;
.LBB0_1889:
	ds_read_b128 v[146:149], v152
	ds_read_b128 v[156:159], v241
	ds_read_b128 v[160:163], v152 offset:2048
	ds_read_b128 v[164:167], v241 offset:2048
	ds_read_b128 v[168:171], v153
	ds_read_b128 v[172:175], v242
	ds_read_b128 v[176:179], v153 offset:2048
	ds_read_b128 v[180:183], v242 offset:2048
	s_add_u32 s16, s14, 0x100
	s_addc_u32 s17, s15, 0
	s_cmp_eq_u32 s44, 60
	s_cselect_b32 s21, s5, s17
	s_cselect_b32 s20, s4, s16
	s_cselect_b32 s19, s13, s43
	s_cselect_b32 s18, s12, s42
	v_lshl_add_u64 v[216:217], s[14:15], 0, v[138:139]
	s_add_i32 m0, s26, 0xc000
	ds_read_b128 v[184:187], v154
	ds_read_b128 v[188:191], v243
	ds_read_b128 v[192:195], v154 offset:2048
	ds_read_b128 v[196:199], v243 offset:2048
	ds_read_b128 v[200:203], v154 offset:4096
	ds_read_b128 v[204:207], v243 offset:4096
	ds_read_b128 v[208:211], v154 offset:6144
	ds_read_b128 v[212:215], v243 offset:6144
	global_load_lds_dwordx4 v[216:217], off
	v_lshl_add_u64 v[216:217], s[14:15], 0, v[140:141]
	s_add_i32 m0, s26, 0xe000
	s_nop 0
	global_load_lds_dwordx4 v[216:217], off
	s_waitcnt vmcnt(8)
	s_waitcnt lgkmcnt(0)
	s_barrier
	s_setprio 1
	s_waitcnt lgkmcnt(0)
	v_mfma_f32_16x16x32_bf16 v[126:129], v[146:149], v[184:187], v[126:129]
	v_mfma_f32_16x16x32_bf16 v[122:125], v[160:163], v[184:187], v[122:125]
	v_mfma_f32_16x16x32_bf16 v[110:113], v[146:149], v[192:195], v[110:113]
	v_mfma_f32_16x16x32_bf16 v[106:109], v[160:163], v[192:195], v[106:109]
	v_mfma_f32_16x16x32_bf16 v[94:97], v[146:149], v[200:203], v[94:97]
	v_mfma_f32_16x16x32_bf16 v[90:93], v[160:163], v[200:203], v[90:93]
	v_mfma_f32_16x16x32_bf16 v[78:81], v[146:149], v[208:211], v[78:81]
	v_mfma_f32_16x16x32_bf16 v[74:77], v[160:163], v[208:211], v[74:77]
	v_mfma_f32_16x16x32_bf16 v[126:129], v[156:159], v[188:191], v[126:129]
	v_mfma_f32_16x16x32_bf16 v[122:125], v[164:167], v[188:191], v[122:125]
	v_mfma_f32_16x16x32_bf16 v[110:113], v[156:159], v[196:199], v[110:113]
	v_mfma_f32_16x16x32_bf16 v[106:109], v[164:167], v[196:199], v[106:109]
	v_mfma_f32_16x16x32_bf16 v[94:97], v[156:159], v[204:207], v[94:97]
	v_mfma_f32_16x16x32_bf16 v[90:93], v[164:167], v[204:207], v[90:93]
	v_mfma_f32_16x16x32_bf16 v[78:81], v[156:159], v[212:215], v[78:81]
	v_mfma_f32_16x16x32_bf16 v[74:77], v[164:167], v[212:215], v[74:77]
	s_setprio 0
	s_setprio 1
	v_mfma_f32_16x16x32_bf16 v[118:121], v[168:171], v[184:187], v[118:121]
	v_mfma_f32_16x16x32_bf16 v[114:117], v[176:179], v[184:187], v[114:117]
	v_mfma_f32_16x16x32_bf16 v[102:105], v[168:171], v[192:195], v[102:105]
	v_mfma_f32_16x16x32_bf16 v[98:101], v[176:179], v[192:195], v[98:101]
	v_mfma_f32_16x16x32_bf16 v[86:89], v[168:171], v[200:203], v[86:89]
	v_mfma_f32_16x16x32_bf16 v[82:85], v[176:179], v[200:203], v[82:85]
	v_mfma_f32_16x16x32_bf16 v[70:73], v[168:171], v[208:211], v[70:73]
	v_mfma_f32_16x16x32_bf16 v[66:69], v[176:179], v[208:211], v[66:69]
	v_mfma_f32_16x16x32_bf16 v[118:121], v[172:175], v[188:191], v[118:121]
	v_mfma_f32_16x16x32_bf16 v[114:117], v[180:183], v[188:191], v[114:117]
	v_mfma_f32_16x16x32_bf16 v[102:105], v[172:175], v[196:199], v[102:105]
	v_mfma_f32_16x16x32_bf16 v[98:101], v[180:183], v[196:199], v[98:101]
	v_mfma_f32_16x16x32_bf16 v[86:89], v[172:175], v[204:207], v[86:89]
	v_mfma_f32_16x16x32_bf16 v[82:85], v[180:183], v[204:207], v[82:85]
	v_mfma_f32_16x16x32_bf16 v[70:73], v[172:175], v[212:215], v[70:73]
	v_mfma_f32_16x16x32_bf16 v[66:69], v[180:183], v[212:215], v[66:69]
	s_setprio 0
	s_barrier
	s_add_i32 s14, s35, s2
	v_lshl_add_u64 v[216:217], s[18:19], 0, v[134:135]
	s_mov_b32 m0, s14
	ds_read_b128 v[184:187], v154 offset:16384
	ds_read_b128 v[188:191], v243 offset:16384
	ds_read_b128 v[192:195], v154 offset:18432
	ds_read_b128 v[196:199], v243 offset:18432
	ds_read_b128 v[200:203], v154 offset:20480
	ds_read_b128 v[204:207], v243 offset:20480
	ds_read_b128 v[208:211], v154 offset:22528
	ds_read_b128 v[212:215], v243 offset:22528
	global_load_lds_dwordx4 v[216:217], off
	s_add_i32 m0, s14, 0x2000
	s_add_u32 s14, s18, 0x108000
	v_lshl_add_u64 v[218:219], s[18:19], 0, v[130:131]
	s_addc_u32 s15, s19, 0
	s_add_i32 s45, s36, s2
	global_load_lds_dwordx4 v[218:219], off
	v_lshl_add_u64 v[220:221], s[14:15], 0, v[134:135]
	s_mov_b32 m0, s45
	v_lshl_add_u64 v[222:223], s[20:21], 0, v[132:133]
	global_load_lds_dwordx4 v[220:221], off
	v_lshl_add_u64 v[220:221], s[14:15], 0, v[130:131]
	s_add_i32 m0, s45, 0x2000
	s_nop 0
	global_load_lds_dwordx4 v[220:221], off
	v_lshl_add_u64 v[220:221], s[20:21], 0, v[136:137]
	s_mov_b32 m0, s26
	s_nop 0
	global_load_lds_dwordx4 v[220:221], off
	s_mov_b32 m0, s27
	s_nop 0
	global_load_lds_dwordx4 v[222:223], off
	s_waitcnt vmcnt(8)
	s_waitcnt lgkmcnt(0)
	s_barrier
; #define PG8_STAGE(bufoff, gbase, voff) do { _Pragma("unroll") for (int _i = 0; _i < 2; ++_i) \
;         __builtin_amdgcn_global_load_lds((const unsigned*)((const char*)(gbase) + (voff)[_i]), (PG8_LAS unsigned*)(lds + (bufoff) + ldsw + _i * 8192), 16, 0, 0); } while (0)
; #define PG8_LDA(dst, b, h) do { _Pragma("unroll") for (int m = 0; m < 4; ++m) _Pragma("unroll") for (int k = 0; k < 2; ++k) dst[m][k] = *(const PG8_LAS bf16x8*)(lds + PG8_SA(b, h) + aoff + m * 2048 + k * 1024); } while (0)
; #define PG8_LDB(dst, b, h) do { _Pragma("unroll") for (int n = 0; n < 2; ++n) _Pragma("unroll") for (int k = 0; k < 2; ++k) dst[n][k] = *(const PG8_LAS bf16x8*)(lds + PG8_SB(b, h) + boff + n * 2048 + k * 1024); } while (0)
; #define PG8_MMA(ai, bj, At, Bt) do { __builtin_amdgcn_s_setprio(1); _Pragma("unroll") for (int m = 0; m < 4; ++m) _Pragma("unroll") for (int n = 0; n < 2; ++n) _Pragma("unroll") for (int k = 0; k < 2; ++k) \
;         acc[ai][bj][m][n] = __builtin_amdgcn_mfma_f32_16x16x32_bf16(Bt[n][k], At[m][k], acc[ai][bj][m][n], 0, 0, 0); __builtin_amdgcn_s_setprio(0); } while (0)
; template <class Epi, class Sched, bool ALIGN_EPI = false, bool SP2 = false>
; __device__ __forceinline__ void gemm_phase(PG8_LAS unsigned char* lds, const Gemm g, const Sched& S, const Epi& E) {
;     ...
;             if constexpr (SP2) {
;             PG8_LDB(B0, 0, 0); PG8_LDB(B1, 0, 1); PG8_SCHED; PG8_LDA(At, 0, 0); PG8_STAGE(PG8_SA(1, 1), a1 + hstep, voffA);
;             PG8_WAIT_V(8); PG8_WAIT_L(0); PG8_BAR; PG8_MMA(0, 0, At, B0); PG8_MMA(0, 1, At, B1); PG8_BAR; PG8_SCHED;
;             PG8_LDA(At, 0, 1); PG8_STAGE(PG8_SB(0, 0), b2, voffB); PG8_STAGE(PG8_SB(0, 1), b2 + hstepB, voffB); PG8_STAGE(PG8_SA(0, 0), a2, voffA);
;             PG8_WAIT_V(8); PG8_WAIT_L(0); PG8_BAR; PG8_MMA(1, 0, At, B0); PG8_MMA(1, 1, At, B1); PG8_BAR; PG8_SCHED;
;             PG8_LDB(B0, 1, 0); PG8_LDB(B1, 1, 1); PG8_SCHED; PG8_LDA(At, 1, 0); PG8_STAGE(PG8_SA(0, 1), a2 + hstep, voffA);
;             PG8_WAIT_V(8); PG8_WAIT_L(0); PG8_BAR; PG8_MMA(0, 0, At, B0); PG8_MMA(0, 1, At, B1); PG8_BAR; PG8_SCHED;
;             PG8_LDA(At, 1, 1); PG8_STAGE(PG8_SB(1, 0), b3, voffB); PG8_STAGE(PG8_SB(1, 1), b3 + hstepB, voffB); PG8_STAGE(PG8_SA(1, 0), a3, voffA);
;             PG8_WAIT_V(8); PG8_WAIT_L(0); PG8_BAR; PG8_MMA(1, 0, At, B0); PG8_MMA(1, 1, At, B1); PG8_BAR; PG8_SCHED;
	s_setprio 1
	s_waitcnt lgkmcnt(0)
	v_mfma_f32_16x16x32_bf16 v[62:65], v[146:149], v[184:187], v[62:65]
	v_mfma_f32_16x16x32_bf16 v[58:61], v[160:163], v[184:187], v[58:61]
	v_mfma_f32_16x16x32_bf16 v[46:49], v[146:149], v[192:195], v[46:49]
	v_mfma_f32_16x16x32_bf16 v[42:45], v[160:163], v[192:195], v[42:45]
	v_mfma_f32_16x16x32_bf16 v[30:33], v[146:149], v[200:203], v[30:33]
	v_mfma_f32_16x16x32_bf16 v[26:29], v[160:163], v[200:203], v[26:29]
	v_mfma_f32_16x16x32_bf16 v[14:17], v[146:149], v[208:211], v[14:17]
	v_mfma_f32_16x16x32_bf16 v[10:13], v[160:163], v[208:211], v[10:13]
	v_mfma_f32_16x16x32_bf16 v[62:65], v[156:159], v[188:191], v[62:65]
	v_mfma_f32_16x16x32_bf16 v[58:61], v[164:167], v[188:191], v[58:61]
	v_mfma_f32_16x16x32_bf16 v[46:49], v[156:159], v[196:199], v[46:49]
	v_mfma_f32_16x16x32_bf16 v[42:45], v[164:167], v[196:199], v[42:45]
	v_mfma_f32_16x16x32_bf16 v[30:33], v[156:159], v[204:207], v[30:33]
	v_mfma_f32_16x16x32_bf16 v[26:29], v[164:167], v[204:207], v[26:29]
	v_mfma_f32_16x16x32_bf16 v[14:17], v[156:159], v[212:215], v[14:17]
	v_mfma_f32_16x16x32_bf16 v[10:13], v[164:167], v[212:215], v[10:13]
	s_setprio 0
	s_setprio 1
	v_mfma_f32_16x16x32_bf16 v[54:57], v[168:171], v[184:187], v[54:57]
	v_mfma_f32_16x16x32_bf16 v[50:53], v[176:179], v[184:187], v[50:53]
	v_mfma_f32_16x16x32_bf16 v[38:41], v[168:171], v[192:195], v[38:41]
	v_mfma_f32_16x16x32_bf16 v[34:37], v[176:179], v[192:195], v[34:37]
	v_mfma_f32_16x16x32_bf16 v[22:25], v[168:171], v[200:203], v[22:25]
	v_mfma_f32_16x16x32_bf16 v[18:21], v[176:179], v[200:203], v[18:21]
	v_mfma_f32_16x16x32_bf16 v[6:9], v[168:171], v[208:211], v[6:9]
	v_mfma_f32_16x16x32_bf16 v[2:5], v[176:179], v[208:211], v[2:5]
	v_mfma_f32_16x16x32_bf16 v[54:57], v[172:175], v[188:191], v[54:57]
	v_mfma_f32_16x16x32_bf16 v[50:53], v[180:183], v[188:191], v[50:53]
	v_mfma_f32_16x16x32_bf16 v[38:41], v[172:175], v[196:199], v[38:41]
	v_mfma_f32_16x16x32_bf16 v[34:37], v[180:183], v[196:199], v[34:37]
	v_mfma_f32_16x16x32_bf16 v[22:25], v[172:175], v[204:207], v[22:25]
	v_mfma_f32_16x16x32_bf16 v[18:21], v[180:183], v[204:207], v[18:21]
	v_mfma_f32_16x16x32_bf16 v[6:9], v[172:175], v[212:215], v[6:9]
	v_mfma_f32_16x16x32_bf16 v[2:5], v[180:183], v[212:215], v[2:5]
	s_setprio 0
	s_barrier
	s_add_i32 s45, 0, 0x18000
	v_add_u32_e32 v155, s45, v150
	v_add_u32_e32 v253, s45, v244
	s_add_i32 s46, 0, 0x1c000
	ds_read_b128 v[146:149], v155
	ds_read_b128 v[156:159], v253
	ds_read_b128 v[160:163], v155 offset:2048
	ds_read_b128 v[164:167], v253 offset:2048
	v_add_u32_e32 v155, s46, v150
	v_add_u32_e32 v253, s46, v244
	ds_read_b128 v[168:171], v155
	ds_read_b128 v[172:175], v253
	ds_read_b128 v[176:179], v155 offset:2048
	ds_read_b128 v[180:183], v253 offset:2048
	s_add_u32 s14, s20, 0x108000
	s_addc_u32 s15, s21, 0
	s_mov_b32 m0, s28
	v_lshl_add_u64 v[224:225], s[14:15], 0, v[136:137]
	ds_read_b128 v[184:187], v154 offset:32768
	ds_read_b128 v[188:191], v243 offset:32768
	ds_read_b128 v[192:195], v154 offset:34816
	ds_read_b128 v[196:199], v243 offset:34816
	ds_read_b128 v[200:203], v154 offset:36864
	ds_read_b128 v[204:207], v243 offset:36864
	ds_read_b128 v[208:211], v154 offset:38912
	ds_read_b128 v[212:215], v243 offset:38912
	global_load_lds_dwordx4 v[224:225], off
	v_lshl_add_u64 v[224:225], s[14:15], 0, v[132:133]
	s_mov_b32 m0, s29
	s_nop 0
	global_load_lds_dwordx4 v[224:225], off
	s_waitcnt vmcnt(8)
	s_waitcnt lgkmcnt(0)
	s_barrier
	s_setprio 1
	s_waitcnt lgkmcnt(0)
	v_mfma_f32_16x16x32_bf16 v[126:129], v[146:149], v[184:187], v[126:129]
	v_mfma_f32_16x16x32_bf16 v[122:125], v[160:163], v[184:187], v[122:125]
	v_mfma_f32_16x16x32_bf16 v[110:113], v[146:149], v[192:195], v[110:113]
	v_mfma_f32_16x16x32_bf16 v[106:109], v[160:163], v[192:195], v[106:109]
	v_mfma_f32_16x16x32_bf16 v[94:97], v[146:149], v[200:203], v[94:97]
	v_mfma_f32_16x16x32_bf16 v[90:93], v[160:163], v[200:203], v[90:93]
	v_mfma_f32_16x16x32_bf16 v[78:81], v[146:149], v[208:211], v[78:81]
	v_mfma_f32_16x16x32_bf16 v[74:77], v[160:163], v[208:211], v[74:77]
	v_mfma_f32_16x16x32_bf16 v[126:129], v[156:159], v[188:191], v[126:129]
	v_mfma_f32_16x16x32_bf16 v[122:125], v[164:167], v[188:191], v[122:125]
	v_mfma_f32_16x16x32_bf16 v[110:113], v[156:159], v[196:199], v[110:113]
	v_mfma_f32_16x16x32_bf16 v[106:109], v[164:167], v[196:199], v[106:109]
	v_mfma_f32_16x16x32_bf16 v[94:97], v[156:159], v[204:207], v[94:97]
	v_mfma_f32_16x16x32_bf16 v[90:93], v[164:167], v[204:207], v[90:93]
	v_mfma_f32_16x16x32_bf16 v[78:81], v[156:159], v[212:215], v[78:81]
	v_mfma_f32_16x16x32_bf16 v[74:77], v[164:167], v[212:215], v[74:77]
	s_setprio 0
	s_setprio 1
	v_mfma_f32_16x16x32_bf16 v[118:121], v[168:171], v[184:187], v[118:121]
	v_mfma_f32_16x16x32_bf16 v[114:117], v[176:179], v[184:187], v[114:117]
	v_mfma_f32_16x16x32_bf16 v[102:105], v[168:171], v[192:195], v[102:105]
	v_mfma_f32_16x16x32_bf16 v[98:101], v[176:179], v[192:195], v[98:101]
	v_mfma_f32_16x16x32_bf16 v[86:89], v[168:171], v[200:203], v[86:89]
	v_mfma_f32_16x16x32_bf16 v[82:85], v[176:179], v[200:203], v[82:85]
	v_mfma_f32_16x16x32_bf16 v[70:73], v[168:171], v[208:211], v[70:73]
	v_mfma_f32_16x16x32_bf16 v[66:69], v[176:179], v[208:211], v[66:69]
	v_mfma_f32_16x16x32_bf16 v[118:121], v[172:175], v[188:191], v[118:121]
	v_mfma_f32_16x16x32_bf16 v[114:117], v[180:183], v[188:191], v[114:117]
	v_mfma_f32_16x16x32_bf16 v[102:105], v[172:175], v[196:199], v[102:105]
	v_mfma_f32_16x16x32_bf16 v[98:101], v[180:183], v[196:199], v[98:101]
	v_mfma_f32_16x16x32_bf16 v[86:89], v[172:175], v[204:207], v[86:89]
	v_mfma_f32_16x16x32_bf16 v[82:85], v[180:183], v[204:207], v[82:85]
	v_mfma_f32_16x16x32_bf16 v[70:73], v[172:175], v[212:215], v[70:73]
	v_mfma_f32_16x16x32_bf16 v[66:69], v[180:183], v[212:215], v[66:69]
	s_setprio 0
	s_barrier
; #define PG8_STAGE(bufoff, gbase, voff) do { _Pragma("unroll") for (int _i = 0; _i < 2; ++_i) \
;         __builtin_amdgcn_global_load_lds((const unsigned*)((const char*)(gbase) + (voff)[_i]), (PG8_LAS unsigned*)(lds + (bufoff) + ldsw + _i * 8192), 16, 0, 0); } while (0)
; #define PG8_LDA(dst, b, h) do { _Pragma("unroll") for (int m = 0; m < 4; ++m) _Pragma("unroll") for (int k = 0; k < 2; ++k) dst[m][k] = *(const PG8_LAS bf16x8*)(lds + PG8_SA(b, h) + aoff + m * 2048 + k * 1024); } while (0)
; #define PG8_LDB(dst, b, h) do { _Pragma("unroll") for (int n = 0; n < 2; ++n) _Pragma("unroll") for (int k = 0; k < 2; ++k) dst[n][k] = *(const PG8_LAS bf16x8*)(lds + PG8_SB(b, h) + boff + n * 2048 + k * 1024); } while (0)
; #define PG8_MMA(ai, bj, At, Bt) do { __builtin_amdgcn_s_setprio(1); _Pragma("unroll") for (int m = 0; m < 4; ++m) _Pragma("unroll") for (int n = 0; n < 2; ++n) _Pragma("unroll") for (int k = 0; k < 2; ++k) \
;         acc[ai][bj][m][n] = __builtin_amdgcn_mfma_f32_16x16x32_bf16(Bt[n][k], At[m][k], acc[ai][bj][m][n], 0, 0, 0); __builtin_amdgcn_s_setprio(0); } while (0)
; template <class Epi, class Sched, bool ALIGN_EPI = false, bool SP2 = false>
; __device__ __forceinline__ void gemm_phase(PG8_LAS unsigned char* lds, const Gemm g, const Sched& S, const Epi& E) {
;     ...
;             if constexpr (SP2) {
;             PG8_LDB(B0, 0, 0); PG8_LDB(B1, 0, 1); PG8_SCHED; PG8_LDA(At, 0, 0); PG8_STAGE(PG8_SA(1, 1), a1 + hstep, voffA);
;             PG8_WAIT_V(8); PG8_WAIT_L(0); PG8_BAR; PG8_MMA(0, 0, At, B0); PG8_MMA(0, 1, At, B1); PG8_BAR; PG8_SCHED;
;             PG8_LDA(At, 0, 1); PG8_STAGE(PG8_SB(0, 0), b2, voffB); PG8_STAGE(PG8_SB(0, 1), b2 + hstepB, voffB); PG8_STAGE(PG8_SA(0, 0), a2, voffA);
;             PG8_WAIT_V(8); PG8_WAIT_L(0); PG8_BAR; PG8_MMA(1, 0, At, B0); PG8_MMA(1, 1, At, B1); PG8_BAR; PG8_SCHED;
;             PG8_LDB(B0, 1, 0); PG8_LDB(B1, 1, 1); PG8_SCHED; PG8_LDA(At, 1, 0); PG8_STAGE(PG8_SA(0, 1), a2 + hstep, voffA);
;             PG8_WAIT_V(8); PG8_WAIT_L(0); PG8_BAR; PG8_MMA(0, 0, At, B0); PG8_MMA(0, 1, At, B1); PG8_BAR; PG8_SCHED;
;             PG8_LDA(At, 1, 1); PG8_STAGE(PG8_SB(1, 0), b3, voffB); PG8_STAGE(PG8_SB(1, 1), b3 + hstepB, voffB); PG8_STAGE(PG8_SA(1, 0), a3, voffA);
;             PG8_WAIT_V(8); PG8_WAIT_L(0); PG8_BAR; PG8_MMA(1, 0, At, B0); PG8_MMA(1, 1, At, B1); PG8_BAR; PG8_SCHED;
	s_add_i32 s14, s45, s2
	v_lshl_add_u64 v[216:217], v[216:217], 0, s[8:9]
	s_mov_b32 m0, s14
	ds_read_b128 v[184:187], v154 offset:49152
	ds_read_b128 v[188:191], v243 offset:49152
	ds_read_b128 v[192:195], v154 offset:51200
	ds_read_b128 v[196:199], v243 offset:51200
	ds_read_b128 v[200:203], v154 offset:53248
	ds_read_b128 v[204:207], v243 offset:53248
	ds_read_b128 v[208:211], v154 offset:55296
	ds_read_b128 v[212:215], v243 offset:55296
	global_load_lds_dwordx4 v[216:217], off
	s_add_i32 m0, s14, 0x2000
	s_add_u32 s14, s18, 0x108080
	v_lshl_add_u64 v[216:217], v[218:219], 0, s[8:9]
	s_addc_u32 s15, s19, 0
	s_add_i32 s18, s46, s2
	global_load_lds_dwordx4 v[216:217], off
	v_lshl_add_u64 v[216:217], s[14:15], 0, v[134:135]
	s_mov_b32 m0, s18
	s_nop 0
	global_load_lds_dwordx4 v[216:217], off
	v_lshl_add_u64 v[216:217], s[14:15], 0, v[130:131]
	s_add_i32 m0, s18, 0x2000
	s_nop 0
	global_load_lds_dwordx4 v[216:217], off
	v_lshl_add_u64 v[216:217], v[220:221], 0, s[8:9]
	s_mov_b32 m0, s31
	s_nop 0
	global_load_lds_dwordx4 v[216:217], off
	v_lshl_add_u64 v[216:217], v[222:223], 0, s[8:9]
	s_mov_b32 m0, s33
	s_nop 0
	global_load_lds_dwordx4 v[216:217], off
	s_waitcnt vmcnt(8)
	s_waitcnt lgkmcnt(0)
	s_barrier
	s_setprio 1
	s_waitcnt lgkmcnt(0)
	v_mfma_f32_16x16x32_bf16 v[62:65], v[146:149], v[184:187], v[62:65]
	v_mfma_f32_16x16x32_bf16 v[58:61], v[160:163], v[184:187], v[58:61]
	v_mfma_f32_16x16x32_bf16 v[46:49], v[146:149], v[192:195], v[46:49]
	v_mfma_f32_16x16x32_bf16 v[42:45], v[160:163], v[192:195], v[42:45]
	v_mfma_f32_16x16x32_bf16 v[30:33], v[146:149], v[200:203], v[30:33]
	v_mfma_f32_16x16x32_bf16 v[26:29], v[160:163], v[200:203], v[26:29]
	v_mfma_f32_16x16x32_bf16 v[14:17], v[146:149], v[208:211], v[14:17]
	v_mfma_f32_16x16x32_bf16 v[10:13], v[160:163], v[208:211], v[10:13]
	v_mfma_f32_16x16x32_bf16 v[62:65], v[156:159], v[188:191], v[62:65]
	v_mfma_f32_16x16x32_bf16 v[58:61], v[164:167], v[188:191], v[58:61]
	v_mfma_f32_16x16x32_bf16 v[46:49], v[156:159], v[196:199], v[46:49]
	v_mfma_f32_16x16x32_bf16 v[42:45], v[164:167], v[196:199], v[42:45]
	v_mfma_f32_16x16x32_bf16 v[30:33], v[156:159], v[204:207], v[30:33]
	v_mfma_f32_16x16x32_bf16 v[26:29], v[164:167], v[204:207], v[26:29]
	v_mfma_f32_16x16x32_bf16 v[14:17], v[156:159], v[212:215], v[14:17]
	v_mfma_f32_16x16x32_bf16 v[10:13], v[164:167], v[212:215], v[10:13]
	s_setprio 0
	s_setprio 1
	v_mfma_f32_16x16x32_bf16 v[54:57], v[168:171], v[184:187], v[54:57]
	v_mfma_f32_16x16x32_bf16 v[50:53], v[176:179], v[184:187], v[50:53]
	v_mfma_f32_16x16x32_bf16 v[38:41], v[168:171], v[192:195], v[38:41]
	v_mfma_f32_16x16x32_bf16 v[34:37], v[176:179], v[192:195], v[34:37]
	v_mfma_f32_16x16x32_bf16 v[22:25], v[168:171], v[200:203], v[22:25]
	v_mfma_f32_16x16x32_bf16 v[18:21], v[176:179], v[200:203], v[18:21]
	v_mfma_f32_16x16x32_bf16 v[6:9], v[168:171], v[208:211], v[6:9]
	v_mfma_f32_16x16x32_bf16 v[2:5], v[176:179], v[208:211], v[2:5]
	v_mfma_f32_16x16x32_bf16 v[54:57], v[172:175], v[188:191], v[54:57]
	v_mfma_f32_16x16x32_bf16 v[50:53], v[180:183], v[188:191], v[50:53]
	v_mfma_f32_16x16x32_bf16 v[38:41], v[172:175], v[196:199], v[38:41]
	v_mfma_f32_16x16x32_bf16 v[34:37], v[180:183], v[196:199], v[34:37]
	v_mfma_f32_16x16x32_bf16 v[22:25], v[172:175], v[204:207], v[22:25]
	v_mfma_f32_16x16x32_bf16 v[18:21], v[180:183], v[204:207], v[18:21]
	v_mfma_f32_16x16x32_bf16 v[6:9], v[172:175], v[212:215], v[6:9]
	v_mfma_f32_16x16x32_bf16 v[2:5], v[180:183], v[212:215], v[2:5]
	s_setprio 0
	s_barrier
	s_add_i32 s44, s44, 2
	s_add_u32 s42, s42, 0x100
	s_addc_u32 s43, s43, 0
	s_cmp_gt_u32 s44, 61
	s_mov_b64 s[14:15], s[16:17]
	s_cbranch_scc0 .LBB0_1889
	s_and_b64 vcc, exec, s[10:11]
	s_cbranch_vccz .LBB0_1892
	s_barrier

; __global__ void __launch_bounds__(NWAVES * 64, 2) hyb_fwd(Args args) {
;     extern __shared__ __attribute__((aligned(16))) unsigned char lds[];
	.amdhsa_kernel _Z7hyb_fwd4Args
		.amdhsa_group_segment_fixed_size 0
		.amdhsa_private_segment_fixed_size 0
		.amdhsa_kernarg_size 424
		.amdhsa_user_sgpr_count 2
		.amdhsa_user_sgpr_dispatch_ptr 0
		.amdhsa_user_sgpr_queue_ptr 0
		.amdhsa_user_sgpr_kernarg_segment_ptr 1
		.amdhsa_user_sgpr_dispatch_id 0
		.amdhsa_user_sgpr_kernarg_preload_length 0
		.amdhsa_user_sgpr_kernarg_preload_offset 0
		.amdhsa_user_sgpr_private_segment_size 0
		.amdhsa_uses_dynamic_stack 0
		.amdhsa_enable_private_segment 0
		.amdhsa_system_sgpr_workgroup_id_x 1
		.amdhsa_system_sgpr_workgroup_id_y 0
		.amdhsa_system_sgpr_workgroup_id_z 0
		.amdhsa_system_sgpr_workgroup_info 0
		.amdhsa_system_vgpr_workitem_id 0
		.amdhsa_next_free_vgpr 256
		.amdhsa_next_free_sgpr 98
		.amdhsa_accum_offset 256
		.amdhsa_reserve_vcc 1
		.amdhsa_float_round_mode_32 0
		.amdhsa_float_round_mode_16_64 0
		.amdhsa_float_denorm_mode_32 3
		.amdhsa_float_denorm_mode_16_64 3
		.amdhsa_dx10_clamp 1
		.amdhsa_ieee_mode 1
		.amdhsa_fp16_overflow 0
		.amdhsa_tg_split 0
		.amdhsa_exception_fp_ieee_invalid_op 0
		.amdhsa_exception_fp_denorm_src 0
		.amdhsa_exception_fp_ieee_div_zero 0
		.amdhsa_exception_fp_ieee_overflow 0
		.amdhsa_exception_fp_ieee_underflow 0
		.amdhsa_exception_fp_ieee_inexact 0
		.amdhsa_exception_int_div_zero 0
	.end_amdhsa_kernel

; __global__ void __launch_bounds__(NWAVES * 64, 2) hyb_fwd(Args args) {
;     extern __shared__ __attribute__((aligned(16))) unsigned char lds[];
amdhsa.kernels:
  - .agpr_count:     0
    .args:
      - .offset:         0
        .size:           168
        .value_kind:     by_value
      - .offset:         168
        .size:           4
        .value_kind:     hidden_block_count_x
      - .offset:         172
        .size:           4
        .value_kind:     hidden_block_count_y
      - .offset:         176
        .size:           4
        .value_kind:     hidden_block_count_z
      - .offset:         180
        .size:           2
        .value_kind:     hidden_group_size_x
      - .offset:         182
        .size:           2
        .value_kind:     hidden_group_size_y
      - .offset:         184
        .size:           2
        .value_kind:     hidden_group_size_z
      - .offset:         186
        .size:           2
        .value_kind:     hidden_remainder_x
      - .offset:         188
        .size:           2
        .value_kind:     hidden_remainder_y
      - .offset:         190
        .size:           2
        .value_kind:     hidden_remainder_z
      - .offset:         208
        .size:           8
        .value_kind:     hidden_global_offset_x
      - .offset:         216
        .size:           8
        .value_kind:     hidden_global_offset_y
      - .offset:         224
        .size:           8
        .value_kind:     hidden_global_offset_z
      - .offset:         232
        .size:           2
        .value_kind:     hidden_grid_dims
      - .offset:         288
        .size:           4
        .value_kind:     hidden_dynamic_lds_size
    .group_segment_fixed_size: 0
    .kernarg_segment_align: 8
    .kernarg_segment_size: 424
    .language:       OpenCL C
    .language_version:
      - 2
      - 0
    .max_flat_workgroup_size: 512
    .name:           _Z7hyb_fwd4Args
    .private_segment_fixed_size: 0
    .sgpr_count:     104
    .sgpr_spill_count: 174
    .symbol:         _Z7hyb_fwd4Args.kd
    .uniform_work_group_size: 1
    .uses_dynamic_stack: false
    .vgpr_count:     256
    .vgpr_spill_count: 0
    .wavefront_size: 64
